# P1 mix path (waves 0-3) rewritten: block-uniform token logic in scalar code, 12 loads of a 3-token step issued together
# speedup vs baseline: 1.0138x; 1.0030x over previous
.LBB0_100:
	flat_load_dwordx2 v[0:1], v[68:69] offset:48 sc0 sc1
	flat_load_dwordx2 v[2:3], v[68:69] offset:88 sc0 sc1
	flat_load_dwordx2 v[4:5], v[68:69] sc0 sc1
	flat_load_dwordx2 v[6:7], v[68:69] offset:16 sc0 sc1
	s_waitcnt vmcnt(0)
	s_and_b64 vcc, exec, s[6:7]
	s_waitcnt lgkmcnt(0)
	v_readfirstlane_b32 s5, v1
	v_readfirstlane_b32 s4, v0
	v_readfirstlane_b32 s1, v3
	v_readfirstlane_b32 s0, v2
	v_readfirstlane_b32 s63, v5
	v_readfirstlane_b32 s62, v4
	v_readfirstlane_b32 s65, v7
	v_readfirstlane_b32 s64, v6
	s_cbranch_vccnz .LBB0_99
	v_add_u32_e32 v44, s8, v87
	v_lshlrev_b32_e32 v45, 2, v44
	v_lshlrev_b32_e32 v46, 1, v44
	global_load_dwordx4 v[0:3], v45, s[4:5]
	global_load_dwordx4 v[4:7], v45, s[40:41]
	global_load_dwordx4 v[8:11], v45, s[26:27]
	global_load_dwordx4 v[12:15], v45, s[44:45]
	global_load_dwordx4 v[16:19], v45, s[42:43]
	global_load_dwordx4 v[20:23], v45, s[0:1]
	v_add_u32_e32 v86, 0x2000, v45
	global_load_dwordx4 v[24:27], v86, s[0:1]
	v_add_u32_e32 v86, 0x4000, v45
	global_load_dwordx4 v[28:31], v86, s[0:1]
	v_add_u32_e32 v86, 0x6000, v45
	global_load_dwordx4 v[32:35], v86, s[0:1]
	v_add_u32_e32 v86, 0x8000, v45
	global_load_dwordx4 v[36:39], v86, s[0:1]
	v_add_u32_e32 v86, 0xa000, v45
	global_load_dwordx4 v[40:43], v86, s[0:1]
	s_lshr_b32 s9, s8, 9
	s_lshr_b32 s10, s23, 1
	s_add_u32 s9, s9, s10
	s_cmp_lt_u32 s9, 2
	s_cselect_b32 s10, 63, 0x1fc0
	s_and_b32 s11, s9, 1
	s_cmp_eq_u32 s11, 0
	s_cselect_b32 s11, 0, s10
	s_cmp_lt_u32 s9, 2
	s_cselect_b32 s12, 1, 64
	s_cselect_b32 s13, 0, 0xff
	s_cselect_b32 s14, -1, 1
	s_and_b32 s15, s9, 1
	s_cmp_eq_u32 s15, 0
	s_cselect_b32 s15, -1, 1
	s_mul_i32 s12, s12, s15
	s_sub_u32 s16, s64, 0x4000000
	s_subb_u32 s17, s65, 0
	s_waitcnt vmcnt(0)
	v_pk_add_f32 v[4:5], v[4:5], 1.0 op_sel_hi:[1,0]
	v_pk_add_f32 v[6:7], v[6:7], 1.0 op_sel_hi:[1,0]
	v_pk_add_f32 v[12:13], v[12:13], 1.0 op_sel_hi:[1,0]
	v_pk_add_f32 v[14:15], v[14:15], 1.0 op_sel_hi:[1,0]
	v_pk_mul_f32 v[4:5], v[0:1], v[4:5]
	v_pk_mul_f32 v[6:7], v[2:3], v[6:7]
	v_pk_mul_f32 v[12:13], v[0:1], v[12:13]
	v_pk_mul_f32 v[14:15], v[2:3], v[14:15]
	s_mov_b32 s66, s2
.Lp1_tok_loop:
	s_mov_b32 s67, s66
	s_mov_b32 s70, 1
	s_cmp_lt_u32 s67, 0x2000
	s_cselect_b32 s25, s10, 0xff
	s_cselect_b32 s28, s11, s13
	s_cselect_b32 s29, s12, s14
	s_cselect_b32 s36, s62, s16
	s_cselect_b32 s37, s63, s17
	s_and_b32 s25, s67, s25
	s_cmp_lg_u32 s25, s28
	s_cselect_b32 s29, s29, 0
	s_cselect_b64 s[74:75], -1, 0
	s_add_i32 s33, s67, s29
	s_lshl_b32 s25, s67, 13
	s_lshl_b32 s28, s33, 13
	s_add_u32 s84, s36, s28
	s_addc_u32 s85, s37, 0
	s_add_u32 s36, s36, s25
	s_addc_u32 s37, s37, 0
	s_lshl_b32 s25, s67, 2
	s_lshl_b32 s28, s33, 2
	v_mov_b32_e32 v86, s25
	v_mov_b32_e32 v88, s28
	global_load_dwordx4 v[48:51], v45, s[36:37]
	global_load_dwordx4 v[52:55], v45, s[84:85]
	global_load_dword v76, v86, s[46:47]
	global_load_dword v78, v88, s[46:47]
	s_mul_i32 s25, s30, 1
	s_add_u32 s68, s66, s25
	s_cmp_lt_u32 s68, 0x2100
	s_cselect_b32 s68, s68, s66
	s_cselect_b32 s71, 1, 0
	s_cmp_lt_u32 s68, 0x2000
	s_cselect_b32 s25, s10, 0xff
	s_cselect_b32 s28, s11, s13
	s_cselect_b32 s29, s12, s14
	s_cselect_b32 s36, s62, s16
	s_cselect_b32 s37, s63, s17
	s_and_b32 s25, s68, s25
	s_cmp_lg_u32 s25, s28
	s_cselect_b32 s29, s29, 0
	s_cselect_b64 s[76:77], -1, 0
	s_add_i32 s33, s68, s29
	s_lshl_b32 s25, s68, 13
	s_lshl_b32 s28, s33, 13
	s_add_u32 s84, s36, s28
	s_addc_u32 s85, s37, 0
	s_add_u32 s36, s36, s25
	s_addc_u32 s37, s37, 0
	s_lshl_b32 s25, s68, 2
	s_lshl_b32 s28, s33, 2
	v_mov_b32_e32 v86, s25
	v_mov_b32_e32 v88, s28
	global_load_dwordx4 v[56:59], v45, s[36:37]
	global_load_dwordx4 v[60:63], v45, s[84:85]
	global_load_dword v80, v86, s[46:47]
	global_load_dword v82, v88, s[46:47]
	s_mul_i32 s25, s30, 2
	s_add_u32 s69, s66, s25
	s_cmp_lt_u32 s69, 0x2100
	s_cselect_b32 s69, s69, s66
	s_cselect_b32 s72, 1, 0
	s_cmp_lt_u32 s69, 0x2000
	s_cselect_b32 s25, s10, 0xff
	s_cselect_b32 s28, s11, s13
	s_cselect_b32 s29, s12, s14
	s_cselect_b32 s36, s62, s16
	s_cselect_b32 s37, s63, s17
	s_and_b32 s25, s69, s25
	s_cmp_lg_u32 s25, s28
	s_cselect_b32 s29, s29, 0
	s_cselect_b64 s[78:79], -1, 0
	s_add_i32 s33, s69, s29
	s_lshl_b32 s25, s69, 13
	s_lshl_b32 s28, s33, 13
	s_add_u32 s84, s36, s28
	s_addc_u32 s85, s37, 0
	s_add_u32 s36, s36, s25
	s_addc_u32 s37, s37, 0
	s_lshl_b32 s25, s69, 2
	s_lshl_b32 s28, s33, 2
	v_mov_b32_e32 v86, s25
	v_mov_b32_e32 v88, s28
	global_load_dwordx4 v[64:67], v45, s[36:37]
	global_load_dwordx4 v[72:75], v45, s[84:85]
	global_load_dword v90, v86, s[46:47]
	global_load_dword v92, v88, s[46:47]
	s_waitcnt vmcnt(0)
	s_cmp_lt_u32 s67, 0x2000
	s_cbranch_scc0 .Lp1_ctx0
	v_pk_mul_f32 v[0:1], v[48:49], v[76:77] op_sel_hi:[1,0]
	v_pk_mul_f32 v[2:3], v[50:51], v[76:77] op_sel_hi:[1,0]
	v_pk_mul_f32 v[94:95], v[52:53], v[78:79] op_sel_hi:[1,0]
	v_pk_mul_f32 v[96:97], v[54:55], v[78:79] op_sel_hi:[1,0]
	v_pk_fma_f32 v[0:1], v[0:1], v[4:5], v[8:9]
	v_pk_fma_f32 v[2:3], v[2:3], v[6:7], v[10:11]
	v_pk_fma_f32 v[94:95], v[94:95], v[4:5], v[8:9]
	v_pk_fma_f32 v[96:97], v[96:97], v[6:7], v[10:11]
	v_cndmask_b32_e64 v94, 0, v94, s[74:75]
	v_cndmask_b32_e64 v95, 0, v95, s[74:75]
	v_cndmask_b32_e64 v96, 0, v96, s[74:75]
	v_cndmask_b32_e64 v97, 0, v97, s[74:75]
	v_pk_add_f32 v[94:95], v[94:95], v[0:1] neg_lo:[0,1] neg_hi:[0,1]
	v_pk_add_f32 v[96:97], v[96:97], v[2:3] neg_lo:[0,1] neg_hi:[0,1]
	s_lshl_b32 s25, s67, 12
	v_add_u32_e32 v47, s25, v46
	v_pk_fma_f32 v[98:99], v[94:95], v[20:21], v[0:1]
	v_pk_fma_f32 v[100:101], v[96:97], v[22:23], v[2:3]
	v_cvt_pk_bf16_f32 v102, v98, v99
	v_cvt_pk_bf16_f32 v103, v100, v101
	global_store_dwordx2 v47, v[102:103], s[38:39]
	v_pk_fma_f32 v[98:99], v[94:95], v[24:25], v[0:1]
	v_pk_fma_f32 v[100:101], v[96:97], v[26:27], v[2:3]
	v_cvt_pk_bf16_f32 v102, v98, v99
	v_cvt_pk_bf16_f32 v103, v100, v101
	global_store_dwordx2 v47, v[102:103], s[48:49]
	v_pk_fma_f32 v[98:99], v[94:95], v[28:29], v[0:1]
	v_pk_fma_f32 v[100:101], v[96:97], v[30:31], v[2:3]
	v_cvt_pk_bf16_f32 v102, v98, v99
	v_cvt_pk_bf16_f32 v103, v100, v101
	global_store_dwordx2 v47, v[102:103], s[50:51]
	v_pk_fma_f32 v[98:99], v[94:95], v[32:33], v[0:1]
	v_pk_fma_f32 v[100:101], v[96:97], v[34:35], v[2:3]
	v_cvt_pk_bf16_f32 v102, v98, v99
	v_cvt_pk_bf16_f32 v103, v100, v101
	global_store_dwordx2 v47, v[102:103], s[52:53]
	v_pk_fma_f32 v[98:99], v[94:95], v[36:37], v[0:1]
	v_pk_fma_f32 v[100:101], v[96:97], v[38:39], v[2:3]
	v_cvt_pk_bf16_f32 v102, v98, v99
	v_cvt_pk_bf16_f32 v103, v100, v101
	global_store_dwordx2 v47, v[102:103], s[54:55]
	v_pk_fma_f32 v[98:99], v[94:95], v[40:41], v[0:1]
	v_pk_fma_f32 v[100:101], v[96:97], v[42:43], v[2:3]
	v_cvt_pk_bf16_f32 v102, v98, v99
	v_cvt_pk_bf16_f32 v103, v100, v101
	global_store_dwordx2 v47, v[102:103], s[56:57]
	s_branch .Lp1_done0
.Lp1_ctx0:
	v_pk_mul_f32 v[0:1], v[48:49], v[76:77] op_sel_hi:[1,0]
	v_pk_mul_f32 v[2:3], v[50:51], v[76:77] op_sel_hi:[1,0]
	v_pk_mul_f32 v[94:95], v[52:53], v[78:79] op_sel_hi:[1,0]
	v_pk_mul_f32 v[96:97], v[54:55], v[78:79] op_sel_hi:[1,0]
	v_pk_fma_f32 v[0:1], v[0:1], v[12:13], v[16:17]
	v_pk_fma_f32 v[2:3], v[2:3], v[14:15], v[18:19]
	v_pk_fma_f32 v[94:95], v[94:95], v[12:13], v[16:17]
	v_pk_fma_f32 v[96:97], v[96:97], v[14:15], v[18:19]
	v_cndmask_b32_e64 v94, 0, v94, s[74:75]
	v_cndmask_b32_e64 v95, 0, v95, s[74:75]
	v_cndmask_b32_e64 v96, 0, v96, s[74:75]
	v_cndmask_b32_e64 v97, 0, v97, s[74:75]
	v_pk_add_f32 v[94:95], v[94:95], v[0:1] neg_lo:[0,1] neg_hi:[0,1]
	v_pk_add_f32 v[96:97], v[96:97], v[2:3] neg_lo:[0,1] neg_hi:[0,1]
	s_lshl_b32 s25, s67, 12
	v_add_u32_e32 v47, s25, v46
	v_pk_fma_f32 v[98:99], v[94:95], v[20:21], v[0:1]
	v_pk_fma_f32 v[100:101], v[96:97], v[22:23], v[2:3]
	v_cvt_pk_bf16_f32 v102, v98, v99
	v_cvt_pk_bf16_f32 v103, v100, v101
	global_store_dwordx2 v47, v[102:103], s[38:39]
	v_pk_fma_f32 v[98:99], v[94:95], v[24:25], v[0:1]
	v_pk_fma_f32 v[100:101], v[96:97], v[26:27], v[2:3]
	v_cvt_pk_bf16_f32 v102, v98, v99
	v_cvt_pk_bf16_f32 v103, v100, v101
	global_store_dwordx2 v47, v[102:103], s[48:49]
	v_pk_fma_f32 v[98:99], v[94:95], v[28:29], v[0:1]
	v_pk_fma_f32 v[100:101], v[96:97], v[30:31], v[2:3]
	v_cvt_pk_bf16_f32 v102, v98, v99
	v_cvt_pk_bf16_f32 v103, v100, v101
	global_store_dwordx2 v47, v[102:103], s[50:51]
	v_pk_fma_f32 v[98:99], v[94:95], v[32:33], v[0:1]
	v_pk_fma_f32 v[100:101], v[96:97], v[34:35], v[2:3]
	v_cvt_pk_bf16_f32 v102, v98, v99
	v_cvt_pk_bf16_f32 v103, v100, v101
	global_store_dwordx2 v47, v[102:103], s[52:53]
	v_pk_fma_f32 v[98:99], v[94:95], v[36:37], v[0:1]
	v_pk_fma_f32 v[100:101], v[96:97], v[38:39], v[2:3]
	v_cvt_pk_bf16_f32 v102, v98, v99
	v_cvt_pk_bf16_f32 v103, v100, v101
	global_store_dwordx2 v47, v[102:103], s[54:55]
	v_pk_fma_f32 v[98:99], v[94:95], v[40:41], v[0:1]
	v_pk_fma_f32 v[100:101], v[96:97], v[42:43], v[2:3]
	v_cvt_pk_bf16_f32 v102, v98, v99
	v_cvt_pk_bf16_f32 v103, v100, v101
	global_store_dwordx2 v47, v[102:103], s[56:57]
.Lp1_done0:
	s_cmp_eq_u32 s71, 0
	s_cbranch_scc1 .Lp1_done1
	s_cmp_lt_u32 s68, 0x2000
	s_cbranch_scc0 .Lp1_ctx1
	v_pk_mul_f32 v[0:1], v[56:57], v[80:81] op_sel_hi:[1,0]
	v_pk_mul_f32 v[2:3], v[58:59], v[80:81] op_sel_hi:[1,0]
	v_pk_mul_f32 v[94:95], v[60:61], v[82:83] op_sel_hi:[1,0]
	v_pk_mul_f32 v[96:97], v[62:63], v[82:83] op_sel_hi:[1,0]
	v_pk_fma_f32 v[0:1], v[0:1], v[4:5], v[8:9]
	v_pk_fma_f32 v[2:3], v[2:3], v[6:7], v[10:11]
	v_pk_fma_f32 v[94:95], v[94:95], v[4:5], v[8:9]
	v_pk_fma_f32 v[96:97], v[96:97], v[6:7], v[10:11]
	v_cndmask_b32_e64 v94, 0, v94, s[76:77]
	v_cndmask_b32_e64 v95, 0, v95, s[76:77]
	v_cndmask_b32_e64 v96, 0, v96, s[76:77]
	v_cndmask_b32_e64 v97, 0, v97, s[76:77]
	v_pk_add_f32 v[94:95], v[94:95], v[0:1] neg_lo:[0,1] neg_hi:[0,1]
	v_pk_add_f32 v[96:97], v[96:97], v[2:3] neg_lo:[0,1] neg_hi:[0,1]
	s_lshl_b32 s25, s68, 12
	v_add_u32_e32 v47, s25, v46
	v_pk_fma_f32 v[98:99], v[94:95], v[20:21], v[0:1]
	v_pk_fma_f32 v[100:101], v[96:97], v[22:23], v[2:3]
	v_cvt_pk_bf16_f32 v102, v98, v99
	v_cvt_pk_bf16_f32 v103, v100, v101
	global_store_dwordx2 v47, v[102:103], s[38:39]
	v_pk_fma_f32 v[98:99], v[94:95], v[24:25], v[0:1]
	v_pk_fma_f32 v[100:101], v[96:97], v[26:27], v[2:3]
	v_cvt_pk_bf16_f32 v102, v98, v99
	v_cvt_pk_bf16_f32 v103, v100, v101
	global_store_dwordx2 v47, v[102:103], s[48:49]
	v_pk_fma_f32 v[98:99], v[94:95], v[28:29], v[0:1]
	v_pk_fma_f32 v[100:101], v[96:97], v[30:31], v[2:3]
	v_cvt_pk_bf16_f32 v102, v98, v99
	v_cvt_pk_bf16_f32 v103, v100, v101
	global_store_dwordx2 v47, v[102:103], s[50:51]
	v_pk_fma_f32 v[98:99], v[94:95], v[32:33], v[0:1]
	v_pk_fma_f32 v[100:101], v[96:97], v[34:35], v[2:3]
	v_cvt_pk_bf16_f32 v102, v98, v99
	v_cvt_pk_bf16_f32 v103, v100, v101
	global_store_dwordx2 v47, v[102:103], s[52:53]
	v_pk_fma_f32 v[98:99], v[94:95], v[36:37], v[0:1]
	v_pk_fma_f32 v[100:101], v[96:97], v[38:39], v[2:3]
	v_cvt_pk_bf16_f32 v102, v98, v99
	v_cvt_pk_bf16_f32 v103, v100, v101
	global_store_dwordx2 v47, v[102:103], s[54:55]
	v_pk_fma_f32 v[98:99], v[94:95], v[40:41], v[0:1]
	v_pk_fma_f32 v[100:101], v[96:97], v[42:43], v[2:3]
	v_cvt_pk_bf16_f32 v102, v98, v99
	v_cvt_pk_bf16_f32 v103, v100, v101
	global_store_dwordx2 v47, v[102:103], s[56:57]
	s_branch .Lp1_done1
.Lp1_ctx1:
	v_pk_mul_f32 v[0:1], v[56:57], v[80:81] op_sel_hi:[1,0]
	v_pk_mul_f32 v[2:3], v[58:59], v[80:81] op_sel_hi:[1,0]
	v_pk_mul_f32 v[94:95], v[60:61], v[82:83] op_sel_hi:[1,0]
	v_pk_mul_f32 v[96:97], v[62:63], v[82:83] op_sel_hi:[1,0]
	v_pk_fma_f32 v[0:1], v[0:1], v[12:13], v[16:17]
	v_pk_fma_f32 v[2:3], v[2:3], v[14:15], v[18:19]
	v_pk_fma_f32 v[94:95], v[94:95], v[12:13], v[16:17]
	v_pk_fma_f32 v[96:97], v[96:97], v[14:15], v[18:19]
	v_cndmask_b32_e64 v94, 0, v94, s[76:77]
	v_cndmask_b32_e64 v95, 0, v95, s[76:77]
	v_cndmask_b32_e64 v96, 0, v96, s[76:77]
	v_cndmask_b32_e64 v97, 0, v97, s[76:77]
	v_pk_add_f32 v[94:95], v[94:95], v[0:1] neg_lo:[0,1] neg_hi:[0,1]
	v_pk_add_f32 v[96:97], v[96:97], v[2:3] neg_lo:[0,1] neg_hi:[0,1]
	s_lshl_b32 s25, s68, 12
	v_add_u32_e32 v47, s25, v46
	v_pk_fma_f32 v[98:99], v[94:95], v[20:21], v[0:1]
	v_pk_fma_f32 v[100:101], v[96:97], v[22:23], v[2:3]
	v_cvt_pk_bf16_f32 v102, v98, v99
	v_cvt_pk_bf16_f32 v103, v100, v101
	global_store_dwordx2 v47, v[102:103], s[38:39]
	v_pk_fma_f32 v[98:99], v[94:95], v[24:25], v[0:1]
	v_pk_fma_f32 v[100:101], v[96:97], v[26:27], v[2:3]
	v_cvt_pk_bf16_f32 v102, v98, v99
	v_cvt_pk_bf16_f32 v103, v100, v101
	global_store_dwordx2 v47, v[102:103], s[48:49]
	v_pk_fma_f32 v[98:99], v[94:95], v[28:29], v[0:1]
	v_pk_fma_f32 v[100:101], v[96:97], v[30:31], v[2:3]
	v_cvt_pk_bf16_f32 v102, v98, v99
	v_cvt_pk_bf16_f32 v103, v100, v101
	global_store_dwordx2 v47, v[102:103], s[50:51]
	v_pk_fma_f32 v[98:99], v[94:95], v[32:33], v[0:1]
	v_pk_fma_f32 v[100:101], v[96:97], v[34:35], v[2:3]
	v_cvt_pk_bf16_f32 v102, v98, v99
	v_cvt_pk_bf16_f32 v103, v100, v101
	global_store_dwordx2 v47, v[102:103], s[52:53]
	v_pk_fma_f32 v[98:99], v[94:95], v[36:37], v[0:1]
	v_pk_fma_f32 v[100:101], v[96:97], v[38:39], v[2:3]
	v_cvt_pk_bf16_f32 v102, v98, v99
	v_cvt_pk_bf16_f32 v103, v100, v101
	global_store_dwordx2 v47, v[102:103], s[54:55]
	v_pk_fma_f32 v[98:99], v[94:95], v[40:41], v[0:1]
	v_pk_fma_f32 v[100:101], v[96:97], v[42:43], v[2:3]
	v_cvt_pk_bf16_f32 v102, v98, v99
	v_cvt_pk_bf16_f32 v103, v100, v101
	global_store_dwordx2 v47, v[102:103], s[56:57]
.Lp1_done1:
	s_cmp_eq_u32 s72, 0
	s_cbranch_scc1 .Lp1_done2
	s_cmp_lt_u32 s69, 0x2000
	s_cbranch_scc0 .Lp1_ctx2
	v_pk_mul_f32 v[0:1], v[64:65], v[90:91] op_sel_hi:[1,0]
	v_pk_mul_f32 v[2:3], v[66:67], v[90:91] op_sel_hi:[1,0]
	v_pk_mul_f32 v[94:95], v[72:73], v[92:93] op_sel_hi:[1,0]
	v_pk_mul_f32 v[96:97], v[74:75], v[92:93] op_sel_hi:[1,0]
	v_pk_fma_f32 v[0:1], v[0:1], v[4:5], v[8:9]
	v_pk_fma_f32 v[2:3], v[2:3], v[6:7], v[10:11]
	v_pk_fma_f32 v[94:95], v[94:95], v[4:5], v[8:9]
	v_pk_fma_f32 v[96:97], v[96:97], v[6:7], v[10:11]
	v_cndmask_b32_e64 v94, 0, v94, s[78:79]
	v_cndmask_b32_e64 v95, 0, v95, s[78:79]
	v_cndmask_b32_e64 v96, 0, v96, s[78:79]
	v_cndmask_b32_e64 v97, 0, v97, s[78:79]
	v_pk_add_f32 v[94:95], v[94:95], v[0:1] neg_lo:[0,1] neg_hi:[0,1]
	v_pk_add_f32 v[96:97], v[96:97], v[2:3] neg_lo:[0,1] neg_hi:[0,1]
	s_lshl_b32 s25, s69, 12
	v_add_u32_e32 v47, s25, v46
	v_pk_fma_f32 v[98:99], v[94:95], v[20:21], v[0:1]
	v_pk_fma_f32 v[100:101], v[96:97], v[22:23], v[2:3]
	v_cvt_pk_bf16_f32 v102, v98, v99
	v_cvt_pk_bf16_f32 v103, v100, v101
	global_store_dwordx2 v47, v[102:103], s[38:39]
	v_pk_fma_f32 v[98:99], v[94:95], v[24:25], v[0:1]
	v_pk_fma_f32 v[100:101], v[96:97], v[26:27], v[2:3]
	v_cvt_pk_bf16_f32 v102, v98, v99
	v_cvt_pk_bf16_f32 v103, v100, v101
	global_store_dwordx2 v47, v[102:103], s[48:49]
	v_pk_fma_f32 v[98:99], v[94:95], v[28:29], v[0:1]
	v_pk_fma_f32 v[100:101], v[96:97], v[30:31], v[2:3]
	v_cvt_pk_bf16_f32 v102, v98, v99
	v_cvt_pk_bf16_f32 v103, v100, v101
	global_store_dwordx2 v47, v[102:103], s[50:51]
	v_pk_fma_f32 v[98:99], v[94:95], v[32:33], v[0:1]
	v_pk_fma_f32 v[100:101], v[96:97], v[34:35], v[2:3]
	v_cvt_pk_bf16_f32 v102, v98, v99
	v_cvt_pk_bf16_f32 v103, v100, v101
	global_store_dwordx2 v47, v[102:103], s[52:53]
	v_pk_fma_f32 v[98:99], v[94:95], v[36:37], v[0:1]
	v_pk_fma_f32 v[100:101], v[96:97], v[38:39], v[2:3]
	v_cvt_pk_bf16_f32 v102, v98, v99
	v_cvt_pk_bf16_f32 v103, v100, v101
	global_store_dwordx2 v47, v[102:103], s[54:55]
	v_pk_fma_f32 v[98:99], v[94:95], v[40:41], v[0:1]
	v_pk_fma_f32 v[100:101], v[96:97], v[42:43], v[2:3]
	v_cvt_pk_bf16_f32 v102, v98, v99
	v_cvt_pk_bf16_f32 v103, v100, v101
	global_store_dwordx2 v47, v[102:103], s[56:57]
	s_branch .Lp1_done2
.Lp1_ctx2:
	v_pk_mul_f32 v[0:1], v[64:65], v[90:91] op_sel_hi:[1,0]
	v_pk_mul_f32 v[2:3], v[66:67], v[90:91] op_sel_hi:[1,0]
	v_pk_mul_f32 v[94:95], v[72:73], v[92:93] op_sel_hi:[1,0]
	v_pk_mul_f32 v[96:97], v[74:75], v[92:93] op_sel_hi:[1,0]
	v_pk_fma_f32 v[0:1], v[0:1], v[12:13], v[16:17]
	v_pk_fma_f32 v[2:3], v[2:3], v[14:15], v[18:19]
	v_pk_fma_f32 v[94:95], v[94:95], v[12:13], v[16:17]
	v_pk_fma_f32 v[96:97], v[96:97], v[14:15], v[18:19]
	v_cndmask_b32_e64 v94, 0, v94, s[78:79]
	v_cndmask_b32_e64 v95, 0, v95, s[78:79]
	v_cndmask_b32_e64 v96, 0, v96, s[78:79]
	v_cndmask_b32_e64 v97, 0, v97, s[78:79]
	v_pk_add_f32 v[94:95], v[94:95], v[0:1] neg_lo:[0,1] neg_hi:[0,1]
	v_pk_add_f32 v[96:97], v[96:97], v[2:3] neg_lo:[0,1] neg_hi:[0,1]
	s_lshl_b32 s25, s69, 12
	v_add_u32_e32 v47, s25, v46
	v_pk_fma_f32 v[98:99], v[94:95], v[20:21], v[0:1]
	v_pk_fma_f32 v[100:101], v[96:97], v[22:23], v[2:3]
	v_cvt_pk_bf16_f32 v102, v98, v99
	v_cvt_pk_bf16_f32 v103, v100, v101
	global_store_dwordx2 v47, v[102:103], s[38:39]
	v_pk_fma_f32 v[98:99], v[94:95], v[24:25], v[0:1]
	v_pk_fma_f32 v[100:101], v[96:97], v[26:27], v[2:3]
	v_cvt_pk_bf16_f32 v102, v98, v99
	v_cvt_pk_bf16_f32 v103, v100, v101
	global_store_dwordx2 v47, v[102:103], s[48:49]
	v_pk_fma_f32 v[98:99], v[94:95], v[28:29], v[0:1]
	v_pk_fma_f32 v[100:101], v[96:97], v[30:31], v[2:3]
	v_cvt_pk_bf16_f32 v102, v98, v99
	v_cvt_pk_bf16_f32 v103, v100, v101
	global_store_dwordx2 v47, v[102:103], s[50:51]
	v_pk_fma_f32 v[98:99], v[94:95], v[32:33], v[0:1]
	v_pk_fma_f32 v[100:101], v[96:97], v[34:35], v[2:3]
	v_cvt_pk_bf16_f32 v102, v98, v99
	v_cvt_pk_bf16_f32 v103, v100, v101
	global_store_dwordx2 v47, v[102:103], s[52:53]
	v_pk_fma_f32 v[98:99], v[94:95], v[36:37], v[0:1]
	v_pk_fma_f32 v[100:101], v[96:97], v[38:39], v[2:3]
	v_cvt_pk_bf16_f32 v102, v98, v99
	v_cvt_pk_bf16_f32 v103, v100, v101
	global_store_dwordx2 v47, v[102:103], s[54:55]
	v_pk_fma_f32 v[98:99], v[94:95], v[40:41], v[0:1]
	v_pk_fma_f32 v[100:101], v[96:97], v[42:43], v[2:3]
	v_cvt_pk_bf16_f32 v102, v98, v99
	v_cvt_pk_bf16_f32 v103, v100, v101
	global_store_dwordx2 v47, v[102:103], s[56:57]
.Lp1_done2:
	s_mul_i32 s25, s30, 3
	s_add_u32 s66, s66, s25
	s_cmp_lt_u32 s66, 0x2100
	s_cbranch_scc1 .Lp1_tok_loop
	s_branch .LBB0_99
